# v20: v19 + write-through (sc1) stores for the converted bf16 weights
# speedup vs baseline: 1.0055x; 1.0013x over previous
; #define LAS __attribute__((address_space(3)))
; __device__ __forceinline__ void tr_item(const float* W, int ldn, int col0, int k0, const float* g, bf16* WT, int ldk, int drow0, LAS float* scr, int lane) {
;     ...
;     for (int i = 0; i < 16; ++i) { const int kk = 4 * i + kr; f32x4 v = *(const f32x4*)(W + (size_t)(k0 + kk) * ldn + col0 + n4); if (g) v = v * g[k0 + kk];
;         LAS float* d = scr + kk * 65 + n4; d[0] = v.x; d[1] = v.y; d[2] = v.z; d[3] = v.w; }
.Ltr_gdone:
	global_load_dwordx4 v[146:149], v232, s[2:3] nt
	v_add_u32_e32 v232, s38, v232
	global_load_dwordx4 v[150:153], v232, s[2:3] nt
	v_add_u32_e32 v232, s38, v232
	global_load_dwordx4 v[154:157], v232, s[2:3] nt
	v_add_u32_e32 v232, s38, v232
	global_load_dwordx4 v[158:161], v232, s[2:3] nt
	v_add_u32_e32 v232, s38, v232
	global_load_dwordx4 v[162:165], v232, s[2:3] nt
	v_add_u32_e32 v232, s38, v232
	global_load_dwordx4 v[166:169], v232, s[2:3] nt
	v_add_u32_e32 v232, s38, v232
	global_load_dwordx4 v[170:173], v232, s[2:3] nt
	v_add_u32_e32 v232, s38, v232
	global_load_dwordx4 v[174:177], v232, s[2:3] nt
	v_add_u32_e32 v232, s38, v232
	global_load_dwordx4 v[178:181], v232, s[2:3] nt
	v_add_u32_e32 v232, s38, v232
	global_load_dwordx4 v[182:185], v232, s[2:3] nt
	v_add_u32_e32 v232, s38, v232
	global_load_dwordx4 v[186:189], v232, s[2:3] nt
	v_add_u32_e32 v232, s38, v232
	global_load_dwordx4 v[190:193], v232, s[2:3] nt
	v_add_u32_e32 v232, s38, v232
	global_load_dwordx4 v[114:117], v232, s[2:3] nt
	v_add_u32_e32 v232, s38, v232
	global_load_dwordx4 v[118:121], v232, s[2:3] nt
	v_add_u32_e32 v232, s38, v232
	global_load_dwordx4 v[122:125], v232, s[2:3] nt
	v_add_u32_e32 v232, s38, v232
	global_load_dwordx4 v[126:129], v232, s[2:3] nt
	s_waitcnt vmcnt(15)
	v_mul_f32_e32 v146, v210, v146
	v_mul_f32_e32 v147, v210, v147
	v_mul_f32_e32 v148, v210, v148
	v_mul_f32_e32 v149, v210, v149
	ds_write2_b32 v242, v146, v147 offset1:1
	ds_write2_b32 v242, v148, v149 offset0:2 offset1:3
	v_add_u32_e32 v242, 0x410, v242
	s_waitcnt vmcnt(14)
	v_mul_f32_e32 v150, v211, v150
	v_mul_f32_e32 v151, v211, v151
	v_mul_f32_e32 v152, v211, v152
	v_mul_f32_e32 v153, v211, v153
	ds_write2_b32 v242, v150, v151 offset1:1
	ds_write2_b32 v242, v152, v153 offset0:2 offset1:3
	v_add_u32_e32 v242, 0x410, v242
	s_waitcnt vmcnt(13)
	v_mul_f32_e32 v154, v212, v154
	v_mul_f32_e32 v155, v212, v155
	v_mul_f32_e32 v156, v212, v156
	v_mul_f32_e32 v157, v212, v157
	ds_write2_b32 v242, v154, v155 offset1:1
	ds_write2_b32 v242, v156, v157 offset0:2 offset1:3
	v_add_u32_e32 v242, 0x410, v242
	s_waitcnt vmcnt(12)
	v_mul_f32_e32 v158, v213, v158
	v_mul_f32_e32 v159, v213, v159
	v_mul_f32_e32 v160, v213, v160
	v_mul_f32_e32 v161, v213, v161
	ds_write2_b32 v242, v158, v159 offset1:1
	ds_write2_b32 v242, v160, v161 offset0:2 offset1:3
	v_add_u32_e32 v242, 0x410, v242
	s_waitcnt vmcnt(11)
	v_mul_f32_e32 v162, v214, v162
	v_mul_f32_e32 v163, v214, v163
	v_mul_f32_e32 v164, v214, v164
	v_mul_f32_e32 v165, v214, v165
	ds_write2_b32 v242, v162, v163 offset1:1
	ds_write2_b32 v242, v164, v165 offset0:2 offset1:3
	v_add_u32_e32 v242, 0x410, v242
	s_waitcnt vmcnt(10)
	v_mul_f32_e32 v166, v215, v166
	v_mul_f32_e32 v167, v215, v167
	v_mul_f32_e32 v168, v215, v168
	v_mul_f32_e32 v169, v215, v169
	ds_write2_b32 v242, v166, v167 offset1:1
	ds_write2_b32 v242, v168, v169 offset0:2 offset1:3
	v_add_u32_e32 v242, 0x410, v242
	s_waitcnt vmcnt(9)
	v_mul_f32_e32 v170, v216, v170
	v_mul_f32_e32 v171, v216, v171
	v_mul_f32_e32 v172, v216, v172
	v_mul_f32_e32 v173, v216, v173
	ds_write2_b32 v242, v170, v171 offset1:1
	ds_write2_b32 v242, v172, v173 offset0:2 offset1:3
	v_add_u32_e32 v242, 0x410, v242
	s_waitcnt vmcnt(8)
	v_mul_f32_e32 v174, v217, v174
	v_mul_f32_e32 v175, v217, v175
	v_mul_f32_e32 v176, v217, v176
	v_mul_f32_e32 v177, v217, v177
	ds_write2_b32 v242, v174, v175 offset1:1
	ds_write2_b32 v242, v176, v177 offset0:2 offset1:3
	v_add_u32_e32 v242, 0x410, v242
	s_waitcnt vmcnt(7)
	v_mul_f32_e32 v178, v218, v178
	v_mul_f32_e32 v179, v218, v179
	v_mul_f32_e32 v180, v218, v180
	v_mul_f32_e32 v181, v218, v181
	ds_write2_b32 v242, v178, v179 offset1:1
	ds_write2_b32 v242, v180, v181 offset0:2 offset1:3
	v_add_u32_e32 v242, 0x410, v242
	s_waitcnt vmcnt(6)
	v_mul_f32_e32 v182, v219, v182
	v_mul_f32_e32 v183, v219, v183
	v_mul_f32_e32 v184, v219, v184
	v_mul_f32_e32 v185, v219, v185
	ds_write2_b32 v242, v182, v183 offset1:1
	ds_write2_b32 v242, v184, v185 offset0:2 offset1:3
	v_add_u32_e32 v242, 0x410, v242
	s_waitcnt vmcnt(5)
	v_mul_f32_e32 v186, v220, v186
	v_mul_f32_e32 v187, v220, v187
	v_mul_f32_e32 v188, v220, v188
	v_mul_f32_e32 v189, v220, v189
	ds_write2_b32 v242, v186, v187 offset1:1
	ds_write2_b32 v242, v188, v189 offset0:2 offset1:3
	v_add_u32_e32 v242, 0x410, v242
	s_waitcnt vmcnt(4)
	v_mul_f32_e32 v190, v221, v190
	v_mul_f32_e32 v191, v221, v191
	v_mul_f32_e32 v192, v221, v192
	v_mul_f32_e32 v193, v221, v193
	ds_write2_b32 v242, v190, v191 offset1:1
	ds_write2_b32 v242, v192, v193 offset0:2 offset1:3
	v_add_u32_e32 v242, 0x410, v242
	s_waitcnt vmcnt(3)
; #define LAS __attribute__((address_space(3)))
; __device__ __forceinline__ unsigned pk2(float lo, float hi) { return f2bf(lo) | (f2bf(hi) << 16); }
; #define LDS_WAIT() asm volatile("s_waitcnt lgkmcnt(0)" ::: "memory")
; __device__ __forceinline__ void tr_item(const float* W, int ldn, int col0, int k0, const float* g, bf16* WT, int ldk, int drow0, LAS float* scr, int lane) {
;     ...
;     const int c = lane & 7;
; #pragma unroll
;     for (int j = 0; j < 8; ++j) { const int n = (lane >> 3) + 8 * j; const LAS float* s = scr + (8 * c) * 65 + n;
;         v4u o; o.x = pk2(s[0 * 65], s[1 * 65]); o.y = pk2(s[2 * 65], s[3 * 65]); o.z = pk2(s[4 * 65], s[5 * 65]); o.w = pk2(s[6 * 65], s[7 * 65]);
;         *(v4u*)(WT + (size_t)(drow0 + n) * ldk + k0 + 8 * c) = o; }
;     LDS_WAIT(); asm volatile("" ::: "memory");
	v_mul_f32_e32 v114, v222, v114
	v_mul_f32_e32 v115, v222, v115
	v_mul_f32_e32 v116, v222, v116
	v_mul_f32_e32 v117, v222, v117
	ds_write2_b32 v242, v114, v115 offset1:1
	ds_write2_b32 v242, v116, v117 offset0:2 offset1:3
	v_add_u32_e32 v242, 0x410, v242
	s_waitcnt vmcnt(2)
	v_mul_f32_e32 v118, v223, v118
	v_mul_f32_e32 v119, v223, v119
	v_mul_f32_e32 v120, v223, v120
	v_mul_f32_e32 v121, v223, v121
	ds_write2_b32 v242, v118, v119 offset1:1
	ds_write2_b32 v242, v120, v121 offset0:2 offset1:3
	v_add_u32_e32 v242, 0x410, v242
	s_waitcnt vmcnt(1)
	v_mul_f32_e32 v122, v230, v122
	v_mul_f32_e32 v123, v230, v123
	v_mul_f32_e32 v124, v230, v124
	v_mul_f32_e32 v125, v230, v125
	ds_write2_b32 v242, v122, v123 offset1:1
	ds_write2_b32 v242, v124, v125 offset0:2 offset1:3
	v_add_u32_e32 v242, 0x410, v242
	s_waitcnt vmcnt(0)
	v_mul_f32_e32 v126, v231, v126
	v_mul_f32_e32 v127, v231, v127
	v_mul_f32_e32 v128, v231, v128
	v_mul_f32_e32 v129, v231, v129
	ds_write2_b32 v242, v126, v127 offset1:1
	ds_write2_b32 v242, v128, v129 offset0:2 offset1:3
	s_waitcnt lgkmcnt(0)
	ds_read2_b32 v[146:147], v62 offset0:0 offset1:65
	ds_read2_b32 v[148:149], v62 offset0:130 offset1:195
	ds_read2_b32 v[150:151], v243 offset0:4 offset1:69
	ds_read2_b32 v[152:153], v243 offset0:134 offset1:199
	ds_read2_b32 v[154:155], v62 offset0:8 offset1:73
	ds_read2_b32 v[156:157], v62 offset0:138 offset1:203
	ds_read2_b32 v[158:159], v243 offset0:12 offset1:77
	ds_read2_b32 v[160:161], v243 offset0:142 offset1:207
	ds_read2_b32 v[162:163], v62 offset0:16 offset1:81
	ds_read2_b32 v[164:165], v62 offset0:146 offset1:211
	ds_read2_b32 v[166:167], v243 offset0:20 offset1:85
	ds_read2_b32 v[168:169], v243 offset0:150 offset1:215
	s_waitcnt lgkmcnt(8)
	v_cvt_pk_bf16_f32 v146, v146, v147
	v_cvt_pk_bf16_f32 v147, v148, v149
	v_cvt_pk_bf16_f32 v148, v150, v151
	v_cvt_pk_bf16_f32 v149, v152, v153
	global_store_dwordx4 v244, v[146:149], s[24:25] sc1
	ds_read2_b32 v[170:171], v62 offset0:24 offset1:89
	ds_read2_b32 v[172:173], v62 offset0:154 offset1:219
	ds_read2_b32 v[174:175], v243 offset0:28 offset1:93
	ds_read2_b32 v[176:177], v243 offset0:158 offset1:223
	s_waitcnt lgkmcnt(8)
	v_cvt_pk_bf16_f32 v154, v154, v155
	v_cvt_pk_bf16_f32 v155, v156, v157
	v_cvt_pk_bf16_f32 v156, v158, v159
	v_cvt_pk_bf16_f32 v157, v160, v161
	global_store_dwordx4 v245, v[154:157], s[24:25] sc1
	ds_read2_b32 v[178:179], v62 offset0:32 offset1:97
	ds_read2_b32 v[180:181], v62 offset0:162 offset1:227
	ds_read2_b32 v[182:183], v243 offset0:36 offset1:101
	ds_read2_b32 v[184:185], v243 offset0:166 offset1:231
	s_waitcnt lgkmcnt(8)
	v_cvt_pk_bf16_f32 v162, v162, v163
	v_cvt_pk_bf16_f32 v163, v164, v165
	v_cvt_pk_bf16_f32 v164, v166, v167
	v_cvt_pk_bf16_f32 v165, v168, v169
	global_store_dwordx4 v246, v[162:165], s[24:25] sc1
	ds_read2_b32 v[186:187], v62 offset0:40 offset1:105
	ds_read2_b32 v[188:189], v62 offset0:170 offset1:235
	ds_read2_b32 v[190:191], v243 offset0:44 offset1:109
	ds_read2_b32 v[192:193], v243 offset0:174 offset1:239
	s_waitcnt lgkmcnt(8)
	v_cvt_pk_bf16_f32 v170, v170, v171
	v_cvt_pk_bf16_f32 v171, v172, v173
	v_cvt_pk_bf16_f32 v172, v174, v175
	v_cvt_pk_bf16_f32 v173, v176, v177
	global_store_dwordx4 v247, v[170:173], s[24:25] sc1
	ds_read2_b32 v[114:115], v62 offset0:48 offset1:113
	ds_read2_b32 v[116:117], v62 offset0:178 offset1:243
	ds_read2_b32 v[118:119], v243 offset0:52 offset1:117
	ds_read2_b32 v[120:121], v243 offset0:182 offset1:247
	s_waitcnt lgkmcnt(8)
	v_cvt_pk_bf16_f32 v178, v178, v179
	v_cvt_pk_bf16_f32 v179, v180, v181
	v_cvt_pk_bf16_f32 v180, v182, v183
	v_cvt_pk_bf16_f32 v181, v184, v185
	global_store_dwordx4 v248, v[178:181], s[24:25] sc1
	ds_read2_b32 v[122:123], v62 offset0:56 offset1:121
	ds_read2_b32 v[124:125], v62 offset0:186 offset1:251
	ds_read2_b32 v[126:127], v243 offset0:60 offset1:125
	ds_read2_b32 v[128:129], v243 offset0:190 offset1:255
	s_waitcnt lgkmcnt(8)
	v_cvt_pk_bf16_f32 v186, v186, v187
	v_cvt_pk_bf16_f32 v187, v188, v189
	v_cvt_pk_bf16_f32 v188, v190, v191
	v_cvt_pk_bf16_f32 v189, v192, v193
	global_store_dwordx4 v249, v[186:189], s[24:25] sc1
	s_waitcnt lgkmcnt(4)
	v_cvt_pk_bf16_f32 v114, v114, v115
	v_cvt_pk_bf16_f32 v115, v116, v117
	v_cvt_pk_bf16_f32 v116, v118, v119
	v_cvt_pk_bf16_f32 v117, v120, v121
	global_store_dwordx4 v250, v[114:117], s[24:25] sc1
	s_waitcnt lgkmcnt(0)
	v_cvt_pk_bf16_f32 v122, v122, v123
	v_cvt_pk_bf16_f32 v123, v124, v125
	v_cvt_pk_bf16_f32 v124, v126, v127
	v_cvt_pk_bf16_f32 v125, v128, v129
	global_store_dwordx4 v251, v[122:125], s[24:25] sc1
	s_cmpk_eq_u32 s8, 0x800
	s_cbranch_scc0 .LBB0_22
	s_cmpk_lg_u32 s94, 0
	s_cbranch_scc1 .Ltr_l1
	s_cmpk_ge_u32 s71, 0x1800
	s_cbranch_scc1 .Ltr_hi
	s_addk_i32 s71, 0x800
	s_cmpk_lt_u32 s71, 0x1800
	s_cbranch_scc1 .LBB0_23
	s_cmpk_lt_u32 s10, 0x400
	s_cbranch_scc1 .LBB0_214
	s_sub_u32 s71, s71, 0x400
	s_branch .LBB0_23

; #define LAS __attribute__((address_space(3)))
; __device__ __forceinline__ void tr_item(const float* W, int ldn, int col0, int k0, const float* g, bf16* WT, int ldk, int drow0, LAS float* scr, int lane) {
;     ...
;     for (int i = 0; i < 16; ++i) { const int kk = 4 * i + kr; f32x4 v = *(const f32x4*)(W + (size_t)(k0 + kk) * ldn + col0 + n4); if (g) v = v * g[k0 + kk];
;         LAS float* d = scr + kk * 65 + n4; d[0] = v.x; d[1] = v.y; d[2] = v.z; d[3] = v.w; }
.Lof2_gdone:
	global_load_dwordx4 v[146:149], v232, s[2:3] nt
	v_add_u32_e32 v232, s38, v232
	global_load_dwordx4 v[150:153], v232, s[2:3] nt
	v_add_u32_e32 v232, s38, v232
	global_load_dwordx4 v[154:157], v232, s[2:3] nt
	v_add_u32_e32 v232, s38, v232
	global_load_dwordx4 v[158:161], v232, s[2:3] nt
	v_add_u32_e32 v232, s38, v232
	global_load_dwordx4 v[166:169], v232, s[2:3] nt
	v_add_u32_e32 v232, s38, v232
	global_load_dwordx4 v[170:173], v232, s[2:3] nt
	v_add_u32_e32 v232, s38, v232
	global_load_dwordx4 v[174:177], v232, s[2:3] nt
	v_add_u32_e32 v232, s38, v232
	global_load_dwordx4 v[178:181], v232, s[2:3] nt
	v_add_u32_e32 v232, s38, v232
	global_load_dwordx4 v[182:185], v232, s[2:3] nt
	v_add_u32_e32 v232, s38, v232
	global_load_dwordx4 v[186:189], v232, s[2:3] nt
	v_add_u32_e32 v232, s38, v232
	global_load_dwordx4 v[190:193], v232, s[2:3] nt
	v_add_u32_e32 v232, s38, v232
	global_load_dwordx4 v[108:111], v232, s[2:3] nt
	v_add_u32_e32 v232, s38, v232
	global_load_dwordx4 v[112:115], v232, s[2:3] nt
	v_add_u32_e32 v232, s38, v232
	global_load_dwordx4 v[116:119], v232, s[2:3] nt
	v_add_u32_e32 v232, s38, v232
	global_load_dwordx4 v[120:123], v232, s[2:3] nt
	v_add_u32_e32 v232, s38, v232
	global_load_dwordx4 v[124:127], v232, s[2:3] nt
	s_waitcnt vmcnt(15)
	v_mul_f32_e32 v146, v210, v146
	v_mul_f32_e32 v147, v210, v147
	v_mul_f32_e32 v148, v210, v148
	v_mul_f32_e32 v149, v210, v149
	ds_write2_b32 v242, v146, v147 offset1:1
	ds_write2_b32 v242, v148, v149 offset0:2 offset1:3
	v_add_u32_e32 v242, 0x410, v242
	s_waitcnt vmcnt(14)
	v_mul_f32_e32 v150, v211, v150
	v_mul_f32_e32 v151, v211, v151
	v_mul_f32_e32 v152, v211, v152
	v_mul_f32_e32 v153, v211, v153
	ds_write2_b32 v242, v150, v151 offset1:1
	ds_write2_b32 v242, v152, v153 offset0:2 offset1:3
	v_add_u32_e32 v242, 0x410, v242
	s_waitcnt vmcnt(13)
	v_mul_f32_e32 v154, v212, v154
	v_mul_f32_e32 v155, v212, v155
	v_mul_f32_e32 v156, v212, v156
	v_mul_f32_e32 v157, v212, v157
	ds_write2_b32 v242, v154, v155 offset1:1
	ds_write2_b32 v242, v156, v157 offset0:2 offset1:3
	v_add_u32_e32 v242, 0x410, v242
	s_waitcnt vmcnt(12)
	v_mul_f32_e32 v158, v213, v158
	v_mul_f32_e32 v159, v213, v159
	v_mul_f32_e32 v160, v213, v160
	v_mul_f32_e32 v161, v213, v161
	ds_write2_b32 v242, v158, v159 offset1:1
	ds_write2_b32 v242, v160, v161 offset0:2 offset1:3
	v_add_u32_e32 v242, 0x410, v242
	s_waitcnt vmcnt(11)
	v_mul_f32_e32 v166, v214, v166
	v_mul_f32_e32 v167, v214, v167
	v_mul_f32_e32 v168, v214, v168
	v_mul_f32_e32 v169, v214, v169
	ds_write2_b32 v242, v166, v167 offset1:1
	ds_write2_b32 v242, v168, v169 offset0:2 offset1:3
	v_add_u32_e32 v242, 0x410, v242
	s_waitcnt vmcnt(10)
	v_mul_f32_e32 v170, v215, v170
	v_mul_f32_e32 v171, v215, v171
	v_mul_f32_e32 v172, v215, v172
	v_mul_f32_e32 v173, v215, v173
	ds_write2_b32 v242, v170, v171 offset1:1
	ds_write2_b32 v242, v172, v173 offset0:2 offset1:3
	v_add_u32_e32 v242, 0x410, v242
	s_waitcnt vmcnt(9)
	v_mul_f32_e32 v174, v216, v174
	v_mul_f32_e32 v175, v216, v175
	v_mul_f32_e32 v176, v216, v176
	v_mul_f32_e32 v177, v216, v177
	ds_write2_b32 v242, v174, v175 offset1:1
	ds_write2_b32 v242, v176, v177 offset0:2 offset1:3
	v_add_u32_e32 v242, 0x410, v242
	s_waitcnt vmcnt(8)
	v_mul_f32_e32 v178, v217, v178
	v_mul_f32_e32 v179, v217, v179
	v_mul_f32_e32 v180, v217, v180
	v_mul_f32_e32 v181, v217, v181
	ds_write2_b32 v242, v178, v179 offset1:1
	ds_write2_b32 v242, v180, v181 offset0:2 offset1:3
	v_add_u32_e32 v242, 0x410, v242
	s_waitcnt vmcnt(7)
	v_mul_f32_e32 v182, v218, v182
	v_mul_f32_e32 v183, v218, v183
	v_mul_f32_e32 v184, v218, v184
	v_mul_f32_e32 v185, v218, v185
	ds_write2_b32 v242, v182, v183 offset1:1
	ds_write2_b32 v242, v184, v185 offset0:2 offset1:3
	v_add_u32_e32 v242, 0x410, v242
	s_waitcnt vmcnt(6)
	v_mul_f32_e32 v186, v219, v186
	v_mul_f32_e32 v187, v219, v187
	v_mul_f32_e32 v188, v219, v188
	v_mul_f32_e32 v189, v219, v189
	ds_write2_b32 v242, v186, v187 offset1:1
	ds_write2_b32 v242, v188, v189 offset0:2 offset1:3
	v_add_u32_e32 v242, 0x410, v242
	s_waitcnt vmcnt(5)
	v_mul_f32_e32 v190, v220, v190
	v_mul_f32_e32 v191, v220, v191
	v_mul_f32_e32 v192, v220, v192
	v_mul_f32_e32 v193, v220, v193
	ds_write2_b32 v242, v190, v191 offset1:1
	ds_write2_b32 v242, v192, v193 offset0:2 offset1:3
	v_add_u32_e32 v242, 0x410, v242
	s_waitcnt vmcnt(4)
	v_mul_f32_e32 v108, v221, v108
	v_mul_f32_e32 v109, v221, v109
	v_mul_f32_e32 v110, v221, v110
	v_mul_f32_e32 v111, v221, v111
	ds_write2_b32 v242, v108, v109 offset1:1
	ds_write2_b32 v242, v110, v111 offset0:2 offset1:3
	v_add_u32_e32 v242, 0x410, v242
	s_waitcnt vmcnt(3)
; #define LAS __attribute__((address_space(3)))
; __device__ __forceinline__ unsigned pk2(float lo, float hi) { return f2bf(lo) | (f2bf(hi) << 16); }
; #define LDS_WAIT() asm volatile("s_waitcnt lgkmcnt(0)" ::: "memory")
; __device__ __forceinline__ void tr_item(const float* W, int ldn, int col0, int k0, const float* g, bf16* WT, int ldk, int drow0, LAS float* scr, int lane) {
;     ...
;     const int c = lane & 7;
; #pragma unroll
;     for (int j = 0; j < 8; ++j) { const int n = (lane >> 3) + 8 * j; const LAS float* s = scr + (8 * c) * 65 + n;
;         v4u o; o.x = pk2(s[0 * 65], s[1 * 65]); o.y = pk2(s[2 * 65], s[3 * 65]); o.z = pk2(s[4 * 65], s[5 * 65]); o.w = pk2(s[6 * 65], s[7 * 65]);
;         *(v4u*)(WT + (size_t)(drow0 + n) * ldk + k0 + 8 * c) = o; }
;     LDS_WAIT(); asm volatile("" ::: "memory");
	v_mul_f32_e32 v112, v222, v112
	v_mul_f32_e32 v113, v222, v113
	v_mul_f32_e32 v114, v222, v114
	v_mul_f32_e32 v115, v222, v115
	ds_write2_b32 v242, v112, v113 offset1:1
	ds_write2_b32 v242, v114, v115 offset0:2 offset1:3
	v_add_u32_e32 v242, 0x410, v242
	s_waitcnt vmcnt(2)
	v_mul_f32_e32 v116, v223, v116
	v_mul_f32_e32 v117, v223, v117
	v_mul_f32_e32 v118, v223, v118
	v_mul_f32_e32 v119, v223, v119
	ds_write2_b32 v242, v116, v117 offset1:1
	ds_write2_b32 v242, v118, v119 offset0:2 offset1:3
	v_add_u32_e32 v242, 0x410, v242
	s_waitcnt vmcnt(1)
	v_mul_f32_e32 v120, v230, v120
	v_mul_f32_e32 v121, v230, v121
	v_mul_f32_e32 v122, v230, v122
	v_mul_f32_e32 v123, v230, v123
	ds_write2_b32 v242, v120, v121 offset1:1
	ds_write2_b32 v242, v122, v123 offset0:2 offset1:3
	v_add_u32_e32 v242, 0x410, v242
	s_waitcnt vmcnt(0)
	v_mul_f32_e32 v124, v231, v124
	v_mul_f32_e32 v125, v231, v125
	v_mul_f32_e32 v126, v231, v126
	v_mul_f32_e32 v127, v231, v127
	ds_write2_b32 v242, v124, v125 offset1:1
	ds_write2_b32 v242, v126, v127 offset0:2 offset1:3
	s_waitcnt lgkmcnt(0)
	ds_read2_b32 v[146:147], v48 offset0:0 offset1:65
	ds_read2_b32 v[148:149], v48 offset0:130 offset1:195
	ds_read2_b32 v[150:151], v243 offset0:4 offset1:69
	ds_read2_b32 v[152:153], v243 offset0:134 offset1:199
	ds_read2_b32 v[154:155], v48 offset0:8 offset1:73
	ds_read2_b32 v[156:157], v48 offset0:138 offset1:203
	ds_read2_b32 v[158:159], v243 offset0:12 offset1:77
	ds_read2_b32 v[160:161], v243 offset0:142 offset1:207
	ds_read2_b32 v[166:167], v48 offset0:16 offset1:81
	ds_read2_b32 v[168:169], v48 offset0:146 offset1:211
	ds_read2_b32 v[170:171], v243 offset0:20 offset1:85
	ds_read2_b32 v[172:173], v243 offset0:150 offset1:215
	s_waitcnt lgkmcnt(8)
	v_cvt_pk_bf16_f32 v146, v146, v147
	v_cvt_pk_bf16_f32 v147, v148, v149
	v_cvt_pk_bf16_f32 v148, v150, v151
	v_cvt_pk_bf16_f32 v149, v152, v153
	global_store_dwordx4 v244, v[146:149], s[24:25] sc1
	ds_read2_b32 v[174:175], v48 offset0:24 offset1:89
	ds_read2_b32 v[176:177], v48 offset0:154 offset1:219
	ds_read2_b32 v[178:179], v243 offset0:28 offset1:93
	ds_read2_b32 v[180:181], v243 offset0:158 offset1:223
	s_waitcnt lgkmcnt(8)
	v_cvt_pk_bf16_f32 v154, v154, v155
	v_cvt_pk_bf16_f32 v155, v156, v157
	v_cvt_pk_bf16_f32 v156, v158, v159
	v_cvt_pk_bf16_f32 v157, v160, v161
	global_store_dwordx4 v245, v[154:157], s[24:25] sc1
	ds_read2_b32 v[182:183], v48 offset0:32 offset1:97
	ds_read2_b32 v[184:185], v48 offset0:162 offset1:227
	ds_read2_b32 v[186:187], v243 offset0:36 offset1:101
	ds_read2_b32 v[188:189], v243 offset0:166 offset1:231
	s_waitcnt lgkmcnt(8)
	v_cvt_pk_bf16_f32 v166, v166, v167
	v_cvt_pk_bf16_f32 v167, v168, v169
	v_cvt_pk_bf16_f32 v168, v170, v171
	v_cvt_pk_bf16_f32 v169, v172, v173
	global_store_dwordx4 v246, v[166:169], s[24:25] sc1
	ds_read2_b32 v[108:109], v48 offset0:40 offset1:105
	ds_read2_b32 v[110:111], v48 offset0:170 offset1:235
	ds_read2_b32 v[112:113], v243 offset0:44 offset1:109
	ds_read2_b32 v[114:115], v243 offset0:174 offset1:239
	s_waitcnt lgkmcnt(8)
	v_cvt_pk_bf16_f32 v174, v174, v175
	v_cvt_pk_bf16_f32 v175, v176, v177
	v_cvt_pk_bf16_f32 v176, v178, v179
	v_cvt_pk_bf16_f32 v177, v180, v181
	global_store_dwordx4 v247, v[174:177], s[24:25] sc1
	ds_read2_b32 v[116:117], v48 offset0:48 offset1:113
	ds_read2_b32 v[118:119], v48 offset0:178 offset1:243
	ds_read2_b32 v[120:121], v243 offset0:52 offset1:117
	ds_read2_b32 v[122:123], v243 offset0:182 offset1:247
	s_waitcnt lgkmcnt(8)
	v_cvt_pk_bf16_f32 v182, v182, v183
	v_cvt_pk_bf16_f32 v183, v184, v185
	v_cvt_pk_bf16_f32 v184, v186, v187
	v_cvt_pk_bf16_f32 v185, v188, v189
	global_store_dwordx4 v248, v[182:185], s[24:25] sc1
	ds_read2_b32 v[124:125], v48 offset0:56 offset1:121
	ds_read2_b32 v[126:127], v48 offset0:186 offset1:251
	ds_read2_b32 v[128:129], v243 offset0:60 offset1:125
	ds_read2_b32 v[130:131], v243 offset0:190 offset1:255
	s_waitcnt lgkmcnt(8)
	v_cvt_pk_bf16_f32 v108, v108, v109
	v_cvt_pk_bf16_f32 v109, v110, v111
	v_cvt_pk_bf16_f32 v110, v112, v113
	v_cvt_pk_bf16_f32 v111, v114, v115
	global_store_dwordx4 v249, v[108:111], s[24:25] sc1
	s_waitcnt lgkmcnt(4)
	v_cvt_pk_bf16_f32 v116, v116, v117
	v_cvt_pk_bf16_f32 v117, v118, v119
	v_cvt_pk_bf16_f32 v118, v120, v121
	v_cvt_pk_bf16_f32 v119, v122, v123
	global_store_dwordx4 v250, v[116:119], s[24:25] sc1
	s_waitcnt lgkmcnt(0)
	v_cvt_pk_bf16_f32 v124, v124, v125
	v_cvt_pk_bf16_f32 v125, v126, v127
	v_cvt_pk_bf16_f32 v126, v128, v129
	v_cvt_pk_bf16_f32 v127, v130, v131
	global_store_dwordx4 v251, v[124:127], s[24:25] sc1
	s_addk_i32 s12, 0x300
	s_cmpk_lt_u32 s12, 0x1e40
	s_cbranch_scc1 .Lof2_item

; #define LAS __attribute__((address_space(3)))
; __device__ __forceinline__ void tr_item(const float* W, int ldn, int col0, int k0, const float* g, bf16* WT, int ldk, int drow0, LAS float* scr, int lane) {
;     ...
;     for (int i = 0; i < 16; ++i) { const int kk = 4 * i + kr; f32x4 v = *(const f32x4*)(W + (size_t)(k0 + kk) * ldn + col0 + n4); if (g) v = v * g[k0 + kk];
;         LAS float* d = scr + kk * 65 + n4; d[0] = v.x; d[1] = v.y; d[2] = v.z; d[3] = v.w; }
.Lofl_gdone:
	global_load_dwordx4 v[146:149], v232, s[2:3] nt
	v_add_u32_e32 v232, s38, v232
	global_load_dwordx4 v[150:153], v232, s[2:3] nt
	v_add_u32_e32 v232, s38, v232
	global_load_dwordx4 v[154:157], v232, s[2:3] nt
	v_add_u32_e32 v232, s38, v232
	global_load_dwordx4 v[158:161], v232, s[2:3] nt
	v_add_u32_e32 v232, s38, v232
	global_load_dwordx4 v[166:169], v232, s[2:3] nt
	v_add_u32_e32 v232, s38, v232
	global_load_dwordx4 v[170:173], v232, s[2:3] nt
	v_add_u32_e32 v232, s38, v232
	global_load_dwordx4 v[174:177], v232, s[2:3] nt
	v_add_u32_e32 v232, s38, v232
	global_load_dwordx4 v[178:181], v232, s[2:3] nt
	v_add_u32_e32 v232, s38, v232
	global_load_dwordx4 v[182:185], v232, s[2:3] nt
	v_add_u32_e32 v232, s38, v232
	global_load_dwordx4 v[186:189], v232, s[2:3] nt
	v_add_u32_e32 v232, s38, v232
	global_load_dwordx4 v[190:193], v232, s[2:3] nt
	v_add_u32_e32 v232, s38, v232
	global_load_dwordx4 v[108:111], v232, s[2:3] nt
	v_add_u32_e32 v232, s38, v232
	global_load_dwordx4 v[112:115], v232, s[2:3] nt
	v_add_u32_e32 v232, s38, v232
	global_load_dwordx4 v[116:119], v232, s[2:3] nt
	v_add_u32_e32 v232, s38, v232
	global_load_dwordx4 v[120:123], v232, s[2:3] nt
	v_add_u32_e32 v232, s38, v232
	global_load_dwordx4 v[124:127], v232, s[2:3] nt
	s_waitcnt vmcnt(15)
	v_mul_f32_e32 v146, v210, v146
	v_mul_f32_e32 v147, v210, v147
	v_mul_f32_e32 v148, v210, v148
	v_mul_f32_e32 v149, v210, v149
	ds_write2_b32 v242, v146, v147 offset1:1
	ds_write2_b32 v242, v148, v149 offset0:2 offset1:3
	v_add_u32_e32 v242, 0x410, v242
	s_waitcnt vmcnt(14)
	v_mul_f32_e32 v150, v211, v150
	v_mul_f32_e32 v151, v211, v151
	v_mul_f32_e32 v152, v211, v152
	v_mul_f32_e32 v153, v211, v153
	ds_write2_b32 v242, v150, v151 offset1:1
	ds_write2_b32 v242, v152, v153 offset0:2 offset1:3
	v_add_u32_e32 v242, 0x410, v242
	s_waitcnt vmcnt(13)
	v_mul_f32_e32 v154, v212, v154
	v_mul_f32_e32 v155, v212, v155
	v_mul_f32_e32 v156, v212, v156
	v_mul_f32_e32 v157, v212, v157
	ds_write2_b32 v242, v154, v155 offset1:1
	ds_write2_b32 v242, v156, v157 offset0:2 offset1:3
	v_add_u32_e32 v242, 0x410, v242
	s_waitcnt vmcnt(12)
	v_mul_f32_e32 v158, v213, v158
	v_mul_f32_e32 v159, v213, v159
	v_mul_f32_e32 v160, v213, v160
	v_mul_f32_e32 v161, v213, v161
	ds_write2_b32 v242, v158, v159 offset1:1
	ds_write2_b32 v242, v160, v161 offset0:2 offset1:3
	v_add_u32_e32 v242, 0x410, v242
	s_waitcnt vmcnt(11)
	v_mul_f32_e32 v166, v214, v166
	v_mul_f32_e32 v167, v214, v167
	v_mul_f32_e32 v168, v214, v168
	v_mul_f32_e32 v169, v214, v169
	ds_write2_b32 v242, v166, v167 offset1:1
	ds_write2_b32 v242, v168, v169 offset0:2 offset1:3
	v_add_u32_e32 v242, 0x410, v242
	s_waitcnt vmcnt(10)
	v_mul_f32_e32 v170, v215, v170
	v_mul_f32_e32 v171, v215, v171
	v_mul_f32_e32 v172, v215, v172
	v_mul_f32_e32 v173, v215, v173
	ds_write2_b32 v242, v170, v171 offset1:1
	ds_write2_b32 v242, v172, v173 offset0:2 offset1:3
	v_add_u32_e32 v242, 0x410, v242
	s_waitcnt vmcnt(9)
	v_mul_f32_e32 v174, v216, v174
	v_mul_f32_e32 v175, v216, v175
	v_mul_f32_e32 v176, v216, v176
	v_mul_f32_e32 v177, v216, v177
	ds_write2_b32 v242, v174, v175 offset1:1
	ds_write2_b32 v242, v176, v177 offset0:2 offset1:3
	v_add_u32_e32 v242, 0x410, v242
	s_waitcnt vmcnt(8)
	v_mul_f32_e32 v178, v217, v178
	v_mul_f32_e32 v179, v217, v179
	v_mul_f32_e32 v180, v217, v180
	v_mul_f32_e32 v181, v217, v181
	ds_write2_b32 v242, v178, v179 offset1:1
	ds_write2_b32 v242, v180, v181 offset0:2 offset1:3
	v_add_u32_e32 v242, 0x410, v242
	s_waitcnt vmcnt(7)
	v_mul_f32_e32 v182, v218, v182
	v_mul_f32_e32 v183, v218, v183
	v_mul_f32_e32 v184, v218, v184
	v_mul_f32_e32 v185, v218, v185
	ds_write2_b32 v242, v182, v183 offset1:1
	ds_write2_b32 v242, v184, v185 offset0:2 offset1:3
	v_add_u32_e32 v242, 0x410, v242
	s_waitcnt vmcnt(6)
	v_mul_f32_e32 v186, v219, v186
	v_mul_f32_e32 v187, v219, v187
	v_mul_f32_e32 v188, v219, v188
	v_mul_f32_e32 v189, v219, v189
	ds_write2_b32 v242, v186, v187 offset1:1
	ds_write2_b32 v242, v188, v189 offset0:2 offset1:3
	v_add_u32_e32 v242, 0x410, v242
	s_waitcnt vmcnt(5)
	v_mul_f32_e32 v190, v220, v190
	v_mul_f32_e32 v191, v220, v191
	v_mul_f32_e32 v192, v220, v192
	v_mul_f32_e32 v193, v220, v193
	ds_write2_b32 v242, v190, v191 offset1:1
	ds_write2_b32 v242, v192, v193 offset0:2 offset1:3
	v_add_u32_e32 v242, 0x410, v242
	s_waitcnt vmcnt(4)
	v_mul_f32_e32 v108, v221, v108
	v_mul_f32_e32 v109, v221, v109
	v_mul_f32_e32 v110, v221, v110
	v_mul_f32_e32 v111, v221, v111
	ds_write2_b32 v242, v108, v109 offset1:1
	ds_write2_b32 v242, v110, v111 offset0:2 offset1:3
	v_add_u32_e32 v242, 0x410, v242
	s_waitcnt vmcnt(3)
; #define LAS __attribute__((address_space(3)))
; __device__ __forceinline__ unsigned pk2(float lo, float hi) { return f2bf(lo) | (f2bf(hi) << 16); }
; #define LDS_WAIT() asm volatile("s_waitcnt lgkmcnt(0)" ::: "memory")
; __device__ __forceinline__ void tr_item(const float* W, int ldn, int col0, int k0, const float* g, bf16* WT, int ldk, int drow0, LAS float* scr, int lane) {
;     ...
;     const int c = lane & 7;
; #pragma unroll
;     for (int j = 0; j < 8; ++j) { const int n = (lane >> 3) + 8 * j; const LAS float* s = scr + (8 * c) * 65 + n;
;         v4u o; o.x = pk2(s[0 * 65], s[1 * 65]); o.y = pk2(s[2 * 65], s[3 * 65]); o.z = pk2(s[4 * 65], s[5 * 65]); o.w = pk2(s[6 * 65], s[7 * 65]);
;         *(v4u*)(WT + (size_t)(drow0 + n) * ldk + k0 + 8 * c) = o; }
;     LDS_WAIT(); asm volatile("" ::: "memory");
	v_mul_f32_e32 v112, v222, v112
	v_mul_f32_e32 v113, v222, v113
	v_mul_f32_e32 v114, v222, v114
	v_mul_f32_e32 v115, v222, v115
	ds_write2_b32 v242, v112, v113 offset1:1
	ds_write2_b32 v242, v114, v115 offset0:2 offset1:3
	v_add_u32_e32 v242, 0x410, v242
	s_waitcnt vmcnt(2)
	v_mul_f32_e32 v116, v223, v116
	v_mul_f32_e32 v117, v223, v117
	v_mul_f32_e32 v118, v223, v118
	v_mul_f32_e32 v119, v223, v119
	ds_write2_b32 v242, v116, v117 offset1:1
	ds_write2_b32 v242, v118, v119 offset0:2 offset1:3
	v_add_u32_e32 v242, 0x410, v242
	s_waitcnt vmcnt(1)
	v_mul_f32_e32 v120, v230, v120
	v_mul_f32_e32 v121, v230, v121
	v_mul_f32_e32 v122, v230, v122
	v_mul_f32_e32 v123, v230, v123
	ds_write2_b32 v242, v120, v121 offset1:1
	ds_write2_b32 v242, v122, v123 offset0:2 offset1:3
	v_add_u32_e32 v242, 0x410, v242
	s_waitcnt vmcnt(0)
	v_mul_f32_e32 v124, v231, v124
	v_mul_f32_e32 v125, v231, v125
	v_mul_f32_e32 v126, v231, v126
	v_mul_f32_e32 v127, v231, v127
	ds_write2_b32 v242, v124, v125 offset1:1
	ds_write2_b32 v242, v126, v127 offset0:2 offset1:3
	s_waitcnt lgkmcnt(0)
	ds_read2_b32 v[146:147], v48 offset0:0 offset1:65
	ds_read2_b32 v[148:149], v48 offset0:130 offset1:195
	ds_read2_b32 v[150:151], v243 offset0:4 offset1:69
	ds_read2_b32 v[152:153], v243 offset0:134 offset1:199
	ds_read2_b32 v[154:155], v48 offset0:8 offset1:73
	ds_read2_b32 v[156:157], v48 offset0:138 offset1:203
	ds_read2_b32 v[158:159], v243 offset0:12 offset1:77
	ds_read2_b32 v[160:161], v243 offset0:142 offset1:207
	ds_read2_b32 v[166:167], v48 offset0:16 offset1:81
	ds_read2_b32 v[168:169], v48 offset0:146 offset1:211
	ds_read2_b32 v[170:171], v243 offset0:20 offset1:85
	ds_read2_b32 v[172:173], v243 offset0:150 offset1:215
	s_waitcnt lgkmcnt(8)
	v_cvt_pk_bf16_f32 v146, v146, v147
	v_cvt_pk_bf16_f32 v147, v148, v149
	v_cvt_pk_bf16_f32 v148, v150, v151
	v_cvt_pk_bf16_f32 v149, v152, v153
	global_store_dwordx4 v244, v[146:149], s[24:25] sc1
	ds_read2_b32 v[174:175], v48 offset0:24 offset1:89
	ds_read2_b32 v[176:177], v48 offset0:154 offset1:219
	ds_read2_b32 v[178:179], v243 offset0:28 offset1:93
	ds_read2_b32 v[180:181], v243 offset0:158 offset1:223
	s_waitcnt lgkmcnt(8)
	v_cvt_pk_bf16_f32 v154, v154, v155
	v_cvt_pk_bf16_f32 v155, v156, v157
	v_cvt_pk_bf16_f32 v156, v158, v159
	v_cvt_pk_bf16_f32 v157, v160, v161
	global_store_dwordx4 v245, v[154:157], s[24:25] sc1
	ds_read2_b32 v[182:183], v48 offset0:32 offset1:97
	ds_read2_b32 v[184:185], v48 offset0:162 offset1:227
	ds_read2_b32 v[186:187], v243 offset0:36 offset1:101
	ds_read2_b32 v[188:189], v243 offset0:166 offset1:231
	s_waitcnt lgkmcnt(8)
	v_cvt_pk_bf16_f32 v166, v166, v167
	v_cvt_pk_bf16_f32 v167, v168, v169
	v_cvt_pk_bf16_f32 v168, v170, v171
	v_cvt_pk_bf16_f32 v169, v172, v173
	global_store_dwordx4 v246, v[166:169], s[24:25] sc1
	ds_read2_b32 v[108:109], v48 offset0:40 offset1:105
	ds_read2_b32 v[110:111], v48 offset0:170 offset1:235
	ds_read2_b32 v[112:113], v243 offset0:44 offset1:109
	ds_read2_b32 v[114:115], v243 offset0:174 offset1:239
	s_waitcnt lgkmcnt(8)
	v_cvt_pk_bf16_f32 v174, v174, v175
	v_cvt_pk_bf16_f32 v175, v176, v177
	v_cvt_pk_bf16_f32 v176, v178, v179
	v_cvt_pk_bf16_f32 v177, v180, v181
	global_store_dwordx4 v247, v[174:177], s[24:25] sc1
	ds_read2_b32 v[116:117], v48 offset0:48 offset1:113
	ds_read2_b32 v[118:119], v48 offset0:178 offset1:243
	ds_read2_b32 v[120:121], v243 offset0:52 offset1:117
	ds_read2_b32 v[122:123], v243 offset0:182 offset1:247
	s_waitcnt lgkmcnt(8)
	v_cvt_pk_bf16_f32 v182, v182, v183
	v_cvt_pk_bf16_f32 v183, v184, v185
	v_cvt_pk_bf16_f32 v184, v186, v187
	v_cvt_pk_bf16_f32 v185, v188, v189
	global_store_dwordx4 v248, v[182:185], s[24:25] sc1
	ds_read2_b32 v[124:125], v48 offset0:56 offset1:121
	ds_read2_b32 v[126:127], v48 offset0:186 offset1:251
	ds_read2_b32 v[128:129], v243 offset0:60 offset1:125
	ds_read2_b32 v[130:131], v243 offset0:190 offset1:255
	s_waitcnt lgkmcnt(8)
	v_cvt_pk_bf16_f32 v108, v108, v109
	v_cvt_pk_bf16_f32 v109, v110, v111
	v_cvt_pk_bf16_f32 v110, v112, v113
	v_cvt_pk_bf16_f32 v111, v114, v115
	global_store_dwordx4 v249, v[108:111], s[24:25] sc1
	s_waitcnt lgkmcnt(4)
	v_cvt_pk_bf16_f32 v116, v116, v117
	v_cvt_pk_bf16_f32 v117, v118, v119
	v_cvt_pk_bf16_f32 v118, v120, v121
	v_cvt_pk_bf16_f32 v119, v122, v123
	global_store_dwordx4 v250, v[116:119], s[24:25] sc1
	s_waitcnt lgkmcnt(0)
	v_cvt_pk_bf16_f32 v124, v124, v125
	v_cvt_pk_bf16_f32 v125, v126, v127
	v_cvt_pk_bf16_f32 v126, v128, v129
	v_cvt_pk_bf16_f32 v127, v130, v131
	global_store_dwordx4 v251, v[124:127], s[24:25] sc1
	s_addk_i32 s10, 0x400
	s_cmpk_lt_u32 s10, 0x1600
	s_cbranch_scc1 .Lofl_item
